# st8 row-scaled streaming conversion loop software-pipelined (next trip's loads issued before converting the current)
# speedup vs baseline: 1.0085x; 1.0001x over previous
.LBB0_690:
	s_or_b64 exec, exec, s[2:3]
	v_mov_b32_e32 v4, v185
	s_mov_b32 s0, 0
	s_nop 0
	v_add_u32_e32 v6, s0, v186
	v_ashrrev_i32_e32 v7, 31, v6
	v_lshlrev_b64 v[0:1], 8, v[6:7]
	v_ashrrev_i32_e32 v5, 31, v4
	v_lshl_add_u64 v[0:1], v[0:1], 0, v[4:5]
	s_mov_b64 s[0:1], 0x20000
	v_cmp_gt_u64_e32 vcc, s[0:1], v[0:1]
	s_and_saveexec_b64 s[2:3], vcc
	s_cbranch_execz .LBB0_693
	s_load_dwordx2 s[0:1], s[54:55], 0xc8
	s_load_dwordx2 s[10:11], s[54:55], 0xd8
	v_lshlrev_b64 v[2:3], 13, v[6:7]
	v_lshlrev_b64 v[8:9], 5, v[4:5]
	v_lshlrev_b64 v[6:7], 12, v[6:7]
	s_waitcnt lgkmcnt(0)
	s_add_u32 s6, s0, s16
	s_addc_u32 s7, s1, s17
	s_ashr_i32 s27, s26, 31
	s_lshl_b64 s[0:1], s[26:27], 22
	v_lshl_add_u64 v[2:3], s[0:1], 0, v[2:3]
	v_lshl_add_u64 v[2:3], v[2:3], 0, v[8:9]
	v_lshl_add_u64 v[2:3], s[10:11], 0, v[2:3]
	s_mov_b64 s[0:1], 0x400000
	s_lshl_b64 s[8:9], s[80:81], 8
	v_lshl_add_u64 v[2:3], v[2:3], 0, s[0:1]
	s_lshl_b64 s[10:11], s[80:81], 13
	v_readlane_b32 s0, v255, 24
	v_lshl_add_u64 v[6:7], s[52:53], 0, v[6:7]
	s_add_u32 s0, s0, s64
	v_readlane_b32 s1, v255, 25
	v_lshl_add_u64 v[4:5], v[4:5], 4, v[6:7]
	s_addc_u32 s1, s1, s65
	v_lshl_add_u64 v[4:5], s[0:1], 0, v[4:5]
	s_lshl_b64 s[12:13], s[80:81], 12
	s_mov_b64 s[14:15], 0
	v_lshrrev_b64 v[6:7], 5, v[0:1]
	v_and_b32_e32 v6, -4, v6
	v_lshl_add_u64 v[6:7], s[6:7], 0, v[6:7]
	global_load_dword v14, v[6:7], off
	s_nop 0
	global_load_dwordx4 v[6:9], v[2:3], off offset:16
	global_load_dwordx4 v[10:13], v[2:3], off
.LBB0_692:
	v_lshl_add_u64 v[0:1], v[0:1], 0, s[8:9]
	v_cmp_lt_u64_e32 vcc, s[58:59], v[0:1]
	v_lshl_add_u64 v[2:3], v[2:3], 0, s[10:11]
	s_or_b64 s[14:15], vcc, s[14:15]
	s_waitcnt vmcnt(0)
	v_mov_b32_e32 v64, v6
	v_mov_b32_e32 v65, v7
	v_mov_b32_e32 v66, v8
	v_mov_b32_e32 v67, v9
	v_mov_b32_e32 v68, v10
	v_mov_b32_e32 v69, v11
	v_mov_b32_e32 v70, v12
	v_mov_b32_e32 v71, v13
	v_mov_b32_e32 v72, v14
	s_mov_b64 s[0:1], exec
	s_andn2_b64 exec, exec, s[14:15]
	v_lshrrev_b64 v[6:7], 5, v[0:1]
	v_and_b32_e32 v6, -4, v6
	v_lshl_add_u64 v[6:7], s[6:7], 0, v[6:7]
	global_load_dword v14, v[6:7], off
	s_nop 0
	global_load_dwordx4 v[6:9], v[2:3], off offset:16
	global_load_dwordx4 v[10:13], v[2:3], off
	s_mov_b64 exec, s[0:1]
	v_mul_f32_e32 v64, v72, v64
	v_mul_f32_e32 v68, v72, v68
	v_mul_f32_e32 v69, v72, v69
	v_cvt_pk_bf16_f32 v74, v68, v69
	v_mul_f32_e32 v69, v72, v70
	v_mul_f32_e32 v70, v72, v71
	v_mul_f32_e32 v65, v72, v65
	v_cvt_pk_bf16_f32 v75, v69, v70
	v_cvt_pk_bf16_f32 v76, v64, v65
	v_mul_f32_e32 v64, v72, v66
	v_mul_f32_e32 v65, v72, v67
	v_cvt_pk_bf16_f32 v77, v64, v65
	global_store_dwordx4 v[4:5], v[74:77], off
	v_lshl_add_u64 v[4:5], v[4:5], 0, s[12:13]
	s_andn2_b64 exec, exec, s[14:15]
	s_cbranch_execnz .LBB0_692
